# k38 + quad-seam counter polls use scalar s_load_dword glc (shorter round trip than the vector sc1 load, and independent of vmcnt)
# baseline (speedup 1.0000x reference)
.LBB0_359:
	s_and_saveexec_b64 s[22:23], vcc
	s_cbranch_execz .LBB0_375
	s_xor_b64 s[24:25], s[4:5], -1
	s_and_saveexec_b64 s[4:5], s[24:25]
	s_cbranch_execz .LBB0_374
	s_load_dword s100, s[6:7], 0x0 glc
	s_waitcnt lgkmcnt(0)
	v_sub_u32_e32 v0, s100, v2
	v_cmp_gt_i32_e32 vcc, 0, v0
	s_and_b64 exec, exec, vcc
	s_cbranch_execz .LBB0_374
	s_add_u32 s16, s16, 0x4200
	s_addc_u32 s17, s17, 0
	s_mov_b32 s26, 1
	s_mov_b64 s[24:25], 0
	s_branch .LBB0_364

.LBB0_366:
	s_load_dword s100, s[6:7], 0x0 glc
	s_add_i32 s26, s26, 1
	s_mov_b64 s[46:47], -1
	s_waitcnt lgkmcnt(0)
	v_sub_u32_e32 v0, s100, v2
	v_cmp_lt_i32_e32 vcc, -1, v0
	s_orn2_b64 s[42:43], vcc, exec
	s_branch .LBB0_363

.LBB0_649:
	s_and_saveexec_b64 s[24:25], vcc
	s_cbranch_execz .LBB0_675
	s_xor_b64 s[4:5], s[2:3], -1
	s_and_saveexec_b64 s[2:3], s[4:5]
	s_cbranch_execz .LBB0_674
	s_load_dword s100, s[46:47], 0x0 glc
	s_waitcnt lgkmcnt(0)
	v_sub_u32_e32 v0, s100, v2
	v_cmp_gt_i32_e32 vcc, 0, v0
	s_and_b64 exec, exec, vcc
	s_cbranch_execz .LBB0_674
	s_add_u32 s40, s48, 0x4200
	s_addc_u32 s41, s49, 0
	s_mov_b32 s4, 1
	s_mov_b64 s[42:43], 0
	s_branch .LBB0_654

.LBB0_656:
	s_load_dword s100, s[46:47], 0x0 glc
	s_add_i32 s4, s4, 1
	s_mov_b64 s[58:59], -1
	s_waitcnt lgkmcnt(0)
	v_sub_u32_e32 v0, s100, v2
	v_cmp_lt_i32_e32 vcc, -1, v0
	s_orn2_b64 s[50:51], vcc, exec
	s_branch .LBB0_653

.LBB0_1002:
	s_and_saveexec_b64 s[12:13], vcc
	s_cbranch_execz .LBB0_1019
	s_xor_b64 s[14:15], s[2:3], -1
	s_and_saveexec_b64 s[2:3], s[14:15]
	s_cbranch_execz .LBB0_1018
	s_load_dword s100, s[8:9], 0x0 glc
	s_waitcnt lgkmcnt(0)
	v_sub_u32_e32 v0, s100, v2
	v_cmp_gt_i32_e32 vcc, 0, v0
	s_and_b64 exec, exec, vcc
	s_cbranch_execz .LBB0_1018
	s_add_u32 s10, s10, 0x4200
	s_addc_u32 s11, s11, 0
	s_mov_b32 s26, 1
	s_mov_b64 s[14:15], 0
	s_branch .LBB0_1007

.LBB0_1009:
	s_load_dword s100, s[8:9], 0x0 glc
	s_add_i32 s26, s26, 1
	s_mov_b64 s[24:25], -1
	s_waitcnt lgkmcnt(0)
	v_sub_u32_e32 v0, s100, v2
	v_cmp_lt_i32_e32 vcc, -1, v0
	s_orn2_b64 s[22:23], vcc, exec
	s_branch .LBB0_1006

.LBB0_1727:
	s_and_saveexec_b64 s[14:15], vcc
	s_cbranch_execz .LBB0_1743
	s_xor_b64 s[16:17], s[2:3], -1
	s_and_saveexec_b64 s[2:3], s[16:17]
	s_cbranch_execz .LBB0_1742
	s_load_dword s100, s[6:7], 0x0 glc
	s_waitcnt lgkmcnt(0)
	v_sub_u32_e32 v0, s100, v2
	v_cmp_gt_i32_e32 vcc, 0, v0
	s_and_b64 exec, exec, vcc
	s_cbranch_execz .LBB0_1742
	s_add_u32 s12, s12, 0x4200
	s_addc_u32 s13, s13, 0
	s_mov_b32 s26, 1
	s_mov_b64 s[16:17], 0
	s_branch .LBB0_1732

.LBB0_1734:
	s_load_dword s100, s[6:7], 0x0 glc
	s_add_i32 s26, s26, 1
	s_mov_b64 s[40:41], -1
	s_waitcnt lgkmcnt(0)
	v_sub_u32_e32 v0, s100, v2
	v_cmp_lt_i32_e32 vcc, -1, v0
	s_orn2_b64 s[24:25], vcc, exec
	s_branch .LBB0_1731
